# MLA softmax: cross-half row max via v_permlane32_swap instead of an LDS bpermute round trip
# speedup vs baseline: 1.0023x; 1.0023x over previous
; #define MFMA(a, b, c) __builtin_amdgcn_mfma_f32_32x32x16_bf16((a), (b), (c), 0, 0, 0)
; template <int DQK>
; DI void attn_tile(const u16* __restrict__ q, int ldq, int qpos0, const Seg& s0, const Seg& s1, int nseg, bool has_sink,
;                   float sinkl2, u16* __restrict__ out, int ldo, char* lds) {
;     ...
;   auto compute = [&](int i) {
;     const Seg& sg = (i < nt0) ? s0 : s1;
;     const int off = ((i < nt0) ? i : i - nt0) << 6;
;     f32x16 sa = zero16(), sb = zero16();
; #pragma unroll
;     for (int ks = 0; ks < NKS; ++ks) {
;       bf16x8 a0 = *(const bf16x8*)(Ks + r * KST + ks * 16 + 8 * h);
;       bf16x8 a1 = *(const bf16x8*)(Ks + (32 + r) * KST + ks * 16 + 8 * h);
;       sa = MFMA(a0, qf[ks], sa);
;       sb = MFMA(a1, qf[ks], sb);
;     }
;     ...
;     float mx = sa[0];
; #pragma unroll
;     for (int g = 1; g < 16; ++g) mx = fmaxf(mx, sa[g]);
; #pragma unroll
;     for (int g = 0; g < 16; ++g) mx = fmaxf(mx, sb[g]);
;     mx = fmaxf(mx, __shfl_xor(mx, 32));
;     const float mn = fmaxf(m, mx);
;     const float alpha = __builtin_amdgcn_exp2f(m - mn);
;     m = mn;
;     float ps = 0.f;
; #pragma unroll
;     for (int g = 0; g < 16; ++g) { sa[g] = __builtin_amdgcn_exp2f(sa[g] - mn); ps += sa[g]; }
; #pragma unroll
;     for (int g = 0; g < 16; ++g) { sb[g] = __builtin_amdgcn_exp2f(sb[g] - mn); ps += sb[g]; }
;     l = l * alpha + ps;
.LBB0_602:
	s_add_i32 s22, s22, 2
	ds_read_b128 v[34:37], v130
	ds_read_b128 v[38:41], v130 offset:6656
	ds_read_b128 v[42:45], v130 offset:32
	s_waitcnt lgkmcnt(2)
	v_mfma_f32_32x32x16_bf16 v[50:65], v[34:37], v[66:69], 0
	ds_read_b128 v[34:37], v130 offset:6688
	v_max3_f32 v137, v184, v185, v186
	v_max3_f32 v137, v137, v187, v188
	v_max3_f32 v137, v137, v189, v190
	v_max3_f32 v137, v137, v191, v192
	s_waitcnt lgkmcnt(2)
	v_mfma_f32_32x32x16_bf16 v[218:233], v[38:41], v[66:69], 0
	ds_read_b128 v[38:41], v130 offset:64
	v_max3_f32 v137, v137, v193, v194
	v_max3_f32 v137, v137, v195, v196
	v_max3_f32 v137, v137, v197, v198
	v_max3_f32 v137, v137, v199, v146
	s_waitcnt lgkmcnt(2)
	v_mfma_f32_32x32x16_bf16 v[50:65], v[42:45], v[70:73], v[50:65]
	ds_read_b128 v[42:45], v130 offset:6720
	v_max3_f32 v137, v137, v147, v148
	v_max3_f32 v137, v137, v149, v150
	v_max3_f32 v137, v137, v151, v152
	v_max3_f32 v137, v137, v153, v154
	s_waitcnt lgkmcnt(2)
	v_mfma_f32_32x32x16_bf16 v[218:233], v[34:37], v[70:73], v[218:233]
	ds_read_b128 v[34:37], v130 offset:96
	v_max3_f32 v137, v137, v155, v156
	v_max3_f32 v137, v137, v157, v158
	v_max3_f32 v137, v137, v159, v160
	v_max3_f32 v137, v137, v161, v161
	s_waitcnt lgkmcnt(2)
	v_mfma_f32_32x32x16_bf16 v[50:65], v[38:41], v[74:77], v[50:65]
	ds_read_b128 v[38:41], v130 offset:6752
	v_mov_b32_e32 v139, v137
	s_nop 1
	v_permlane32_swap_b32 v137, v139
	s_nop 1
	s_waitcnt lgkmcnt(2)
	v_mfma_f32_32x32x16_bf16 v[218:233], v[42:45], v[74:77], v[218:233]
	ds_read_b128 v[42:45], v130 offset:128
	v_max3_f32 v134, v135, v137, v139
	v_sub_f32_e32 v141, v135, v134
	v_exp_f32_e32 v140, v141
	v_mov_b32_e32 v144, v134
	s_waitcnt lgkmcnt(2)
	v_mfma_f32_32x32x16_bf16 v[50:65], v[34:37], v[78:81], v[50:65]
	ds_read_b128 v[34:37], v130 offset:6784
	v_mov_b32_e32 v145, v134
	v_sub_f32_e32 v184, v184, v134
	v_sub_f32_e32 v185, v185, v134
	v_sub_f32_e32 v186, v186, v134
	s_waitcnt lgkmcnt(2)
	v_mfma_f32_32x32x16_bf16 v[218:233], v[38:41], v[78:81], v[218:233]
	ds_read_b128 v[38:41], v130 offset:160
	v_sub_f32_e32 v187, v187, v134
	v_sub_f32_e32 v188, v188, v134
	v_sub_f32_e32 v189, v189, v134
	v_sub_f32_e32 v190, v190, v134
	s_waitcnt lgkmcnt(2)
	v_mfma_f32_32x32x16_bf16 v[50:65], v[42:45], v[82:85], v[50:65]
	ds_read_b128 v[42:45], v130 offset:6816
	v_sub_f32_e32 v191, v191, v134
	v_exp_f32_e32 v184, v184
	v_sub_f32_e32 v192, v192, v134
	v_sub_f32_e32 v193, v193, v134
	s_waitcnt lgkmcnt(2)
	v_mfma_f32_32x32x16_bf16 v[218:233], v[34:37], v[82:85], v[218:233]
	v_sub_f32_e32 v194, v194, v134
	v_sub_f32_e32 v195, v195, v134
	v_exp_f32_e32 v185, v185
	v_sub_f32_e32 v196, v196, v134
	s_waitcnt lgkmcnt(1)
	v_mfma_f32_32x32x16_bf16 v[50:65], v[38:41], v[86:89], v[50:65]
	v_sub_f32_e32 v197, v197, v134
	v_sub_f32_e32 v198, v198, v134
	v_sub_f32_e32 v199, v199, v134
	v_exp_f32_e32 v186, v186
	s_waitcnt lgkmcnt(0)
	v_mfma_f32_32x32x16_bf16 v[218:233], v[42:45], v[86:89], v[218:233]
	ds_read_b64_tr_b16 v[46:47], v133 offset:46080
	ds_read_b64_tr_b16 v[48:49], v133 offset:47616
	ds_read_b64_tr_b16 v[200:201], v133 offset:46144
	ds_read_b64_tr_b16 v[202:203], v133 offset:47680
	ds_read_b64_tr_b16 v[204:205], v133 offset:49152
	ds_read_b64_tr_b16 v[206:207], v133 offset:50688
	v_sub_f32_e32 v146, v146, v134
	v_sub_f32_e32 v147, v147, v134
	v_sub_f32_e32 v148, v148, v134
	v_sub_f32_e32 v149, v149, v134
	v_exp_f32_e32 v187, v187
	v_sub_f32_e32 v150, v150, v134
	v_sub_f32_e32 v151, v151, v134
	v_sub_f32_e32 v152, v152, v134
	v_sub_f32_e32 v153, v153, v134
	v_exp_f32_e32 v188, v188
	v_mul_f32_e32 v33, v140, v33
	v_mul_f32_e32 v32, v140, v32
	v_mul_f32_e32 v31, v140, v31
	v_mul_f32_e32 v30, v140, v30
	v_exp_f32_e32 v189, v189
	v_mul_f32_e32 v29, v140, v29
	v_mul_f32_e32 v28, v140, v28
	v_mul_f32_e32 v27, v140, v27
	v_mul_f32_e32 v26, v140, v26
	v_exp_f32_e32 v190, v190
	v_mul_f32_e32 v25, v140, v25
	v_mul_f32_e32 v24, v140, v24
	v_mul_f32_e32 v23, v140, v23
	v_mul_f32_e32 v22, v140, v22
	v_exp_f32_e32 v191, v191
	v_mul_f32_e32 v21, v140, v21
	v_mul_f32_e32 v20, v140, v20
	v_mul_f32_e32 v19, v140, v19
	v_mul_f32_e32 v18, v140, v18
	v_exp_f32_e32 v192, v192
	v_sub_f32_e32 v154, v154, v134
	v_sub_f32_e32 v155, v155, v134
	v_sub_f32_e32 v156, v156, v134
	v_sub_f32_e32 v157, v157, v134
	v_sub_f32_e32 v158, v158, v134
	v_exp_f32_e32 v193, v193
	v_sub_f32_e32 v159, v159, v134
	v_sub_f32_e32 v160, v160, v134
	v_sub_f32_e32 v161, v161, v134
	v_mul_f32_e32 v17, v140, v17
	v_mul_f32_e32 v16, v140, v16
	v_exp_f32_e32 v194, v194
	v_mul_f32_e32 v15, v140, v15
	v_mul_f32_e32 v14, v140, v14
	v_mul_f32_e32 v13, v140, v13
	v_mul_f32_e32 v12, v140, v12
	v_mul_f32_e32 v11, v140, v11
	v_exp_f32_e32 v195, v195
	v_mul_f32_e32 v10, v140, v10
	v_mul_f32_e32 v9, v140, v9
	v_mul_f32_e32 v8, v140, v8
	v_mul_f32_e32 v7, v140, v7
	v_mul_f32_e32 v6, v140, v6
	v_exp_f32_e32 v196, v196
	v_mul_f32_e32 v5, v140, v5
	v_mul_f32_e32 v4, v140, v4
	v_mul_f32_e32 v3, v140, v3
	v_mul_f32_e32 v2, v140, v2
	v_add_f32_e32 v238, v184, v185
	v_exp_f32_e32 v197, v197
	v_add_f32_e32 v238, v238, v186
	v_add_f32_e32 v238, v238, v187
	v_add_f32_e32 v238, v238, v188
	v_add_f32_e32 v238, v238, v189
	v_add_f32_e32 v238, v238, v190
	v_exp_f32_e32 v198, v198
	v_add_f32_e32 v238, v238, v191
	v_cvt_pk_bf16_f32 v184, v184, v185
	v_cvt_pk_bf16_f32 v185, v186, v187
	v_cvt_pk_bf16_f32 v186, v188, v189
	v_cvt_pk_bf16_f32 v187, v190, v191
	v_exp_f32_e32 v199, v199
	s_nop 0
	s_waitcnt lgkmcnt(4)
; #define MFMA(a, b, c) __builtin_amdgcn_mfma_f32_32x32x16_bf16((a), (b), (c), 0, 0, 0)
; #define ATT_VTR(p) __builtin_bit_cast(s16x4, __builtin_amdgcn_ds_read_tr16_b64_v4i16((__attribute__((address_space(3))) v4i16_t*)(p)))
; template <int DQK>
; DI void attn_tile(const u16* __restrict__ q, int ldq, int qpos0, const Seg& s0, const Seg& s1, int nseg, bool has_sink,
;                   float sinkl2, u16* __restrict__ out, int ldo, char* lds) {
;     ...
;     float ps = 0.f;
; #pragma unroll
;     for (int g = 0; g < 16; ++g) { sa[g] = __builtin_amdgcn_exp2f(sa[g] - mn); ps += sa[g]; }
; #pragma unroll
;     for (int g = 0; g < 16; ++g) { sb[g] = __builtin_amdgcn_exp2f(sb[g] - mn); ps += sb[g]; }
;     l = l * alpha + ps;
; #pragma unroll
;     for (int g = 0; g < 16; ++g) { o0[g] *= alpha; o1[g] *= alpha; }
; #pragma unroll
;     for (int kt = 0; kt < 2; ++kt) {
; #pragma unroll
;       for (int s = 0; s < 2; ++s) {
;         const f32x16& sv = kt == 0 ? sa : sb;
;         uint4 pu;
;         pu.x = pack2(sv[8 * s + 0], sv[8 * s + 1]); pu.y = pack2(sv[8 * s + 2], sv[8 * s + 3]);
;         pu.z = pack2(sv[8 * s + 4], sv[8 * s + 5]); pu.w = pack2(sv[8 * s + 6], sv[8 * s + 7]);
;         bf16x8 pf = __builtin_bit_cast(bf16x8, pu);
;         const lds_cptr vp = vp0 + (kt * 32 + 16 * s) * (VST * 2);
;         {
;           s16x4 lo = ATT_VTR(vp);
;           s16x4 hi = ATT_VTR(vp + 8 * VST * 2);
;           bf16x8 vf = __builtin_shufflevector(lo, hi, 0, 1, 2, 3, 4, 5, 6, 7);
;           o0 = MFMA(vf, pf, o0);
;         }
;         {
;           s16x4 lo = ATT_VTR(vp + 64);
;           s16x4 hi = ATT_VTR(vp + 8 * VST * 2 + 64);
;           bf16x8 vf = __builtin_shufflevector(lo, hi, 0, 1, 2, 3, 4, 5, 6, 7);
;           o1 = MFMA(vf, pf, o1);
;         }
;       }
;     }
	v_mfma_f32_32x32x16_bf16 v[18:33], v[46:49], v[184:187], v[18:33]
	ds_read_b64_tr_b16 v[46:47], v133 offset:49216
	ds_read_b64_tr_b16 v[48:49], v133 offset:50752
	s_waitcnt lgkmcnt(4)
	v_mfma_f32_32x32x16_bf16 v[2:17], v[200:203], v[184:187], v[2:17]
	ds_read_b64_tr_b16 v[200:201], v133 offset:52224
	ds_read_b64_tr_b16 v[202:203], v133 offset:53760
	v_exp_f32_e32 v146, v146
	v_add_f32_e32 v238, v238, v192
	v_add_f32_e32 v238, v238, v193
	v_exp_f32_e32 v147, v147
	v_add_f32_e32 v238, v238, v194
	v_add_f32_e32 v238, v238, v195
	v_exp_f32_e32 v148, v148
	v_add_f32_e32 v238, v238, v196
	v_add_f32_e32 v238, v238, v197
	v_exp_f32_e32 v149, v149
	v_add_f32_e32 v238, v238, v198
	v_add_f32_e32 v238, v238, v199
	v_exp_f32_e32 v150, v150
	v_cvt_pk_bf16_f32 v188, v192, v193
	v_cvt_pk_bf16_f32 v189, v194, v195
	v_exp_f32_e32 v151, v151
	v_cvt_pk_bf16_f32 v190, v196, v197
	v_cvt_pk_bf16_f32 v191, v198, v199
	v_exp_f32_e32 v152, v152
	v_exp_f32_e32 v153, v153
	s_nop 0
	s_waitcnt lgkmcnt(4)
	v_mfma_f32_32x32x16_bf16 v[18:33], v[204:207], v[188:191], v[18:33]
	ds_read_b64_tr_b16 v[204:205], v133 offset:52288
	ds_read_b64_tr_b16 v[206:207], v133 offset:53824
	s_waitcnt lgkmcnt(4)
	v_mfma_f32_32x32x16_bf16 v[2:17], v[46:49], v[188:191], v[2:17]
	ds_read_b64_tr_b16 v[46:47], v133 offset:55296
	ds_read_b64_tr_b16 v[48:49], v133 offset:56832
	v_exp_f32_e32 v154, v154
	v_add_f32_e32 v238, v238, v146
	v_add_f32_e32 v238, v238, v147
	v_exp_f32_e32 v155, v155
	v_add_f32_e32 v238, v238, v148
	v_add_f32_e32 v238, v238, v149
	v_exp_f32_e32 v156, v156
	v_add_f32_e32 v238, v238, v150
	v_add_f32_e32 v238, v238, v151
	v_exp_f32_e32 v157, v157
	v_add_f32_e32 v238, v238, v152
	v_add_f32_e32 v238, v238, v153
	v_exp_f32_e32 v158, v158
	v_cvt_pk_bf16_f32 v146, v146, v147
	v_cvt_pk_bf16_f32 v147, v148, v149
	v_exp_f32_e32 v159, v159
	v_cvt_pk_bf16_f32 v148, v150, v151
	v_cvt_pk_bf16_f32 v149, v152, v153
	v_exp_f32_e32 v160, v160
	v_exp_f32_e32 v161, v161
	s_nop 0
	s_waitcnt lgkmcnt(4)
	v_mfma_f32_32x32x16_bf16 v[18:33], v[200:203], v[146:149], v[18:33]
	ds_read_b64_tr_b16 v[200:201], v133 offset:55360
	ds_read_b64_tr_b16 v[202:203], v133 offset:56896
	s_waitcnt lgkmcnt(4)
	v_mfma_f32_32x32x16_bf16 v[2:17], v[204:207], v[146:149], v[2:17]
	v_add_f32_e32 v238, v238, v154
	v_add_f32_e32 v238, v238, v155
	v_add_f32_e32 v238, v238, v156
	v_add_f32_e32 v238, v238, v157
	v_add_f32_e32 v238, v238, v158
	v_add_f32_e32 v238, v238, v159
	v_add_f32_e32 v238, v238, v160
	v_add_f32_e32 v238, v238, v161
	v_cvt_pk_bf16_f32 v150, v154, v155
	v_cvt_pk_bf16_f32 v151, v156, v157
	v_cvt_pk_bf16_f32 v152, v158, v159
	v_cvt_pk_bf16_f32 v153, v160, v161
	s_nop 0
	s_waitcnt lgkmcnt(2)
	v_mfma_f32_32x32x16_bf16 v[18:33], v[46:49], v[150:153], v[18:33]
	s_waitcnt lgkmcnt(0)
	v_mfma_f32_32x32x16_bf16 v[2:17], v[200:203], v[150:153], v[2:17]
	v_fma_f32 v128, v136, v140, v238
	s_cmpk_lt_u32 s27, 0x42
	s_cbranch_scc0 .LBB0_727

; #define MFMA(a, b, c) __builtin_amdgcn_mfma_f32_32x32x16_bf16((a), (b), (c), 0, 0, 0)
; template <int DQK>
; DI void attn_tile(const u16* __restrict__ q, int ldq, int qpos0, const Seg& s0, const Seg& s1, int nseg, bool has_sink,
;                   float sinkl2, u16* __restrict__ out, int ldo, char* lds) {
;     ...
;   auto compute = [&](int i) {
;     const Seg& sg = (i < nt0) ? s0 : s1;
;     const int off = ((i < nt0) ? i : i - nt0) << 6;
;     f32x16 sa = zero16(), sb = zero16();
; #pragma unroll
;     for (int ks = 0; ks < NKS; ++ks) {
;       bf16x8 a0 = *(const bf16x8*)(Ks + r * KST + ks * 16 + 8 * h);
;       bf16x8 a1 = *(const bf16x8*)(Ks + (32 + r) * KST + ks * 16 + 8 * h);
;       sa = MFMA(a0, qf[ks], sa);
;       sb = MFMA(a1, qf[ks], sb);
;     }
;     ...
;     float mx = sa[0];
; #pragma unroll
;     for (int g = 1; g < 16; ++g) mx = fmaxf(mx, sa[g]);
; #pragma unroll
;     for (int g = 0; g < 16; ++g) mx = fmaxf(mx, sb[g]);
;     mx = fmaxf(mx, __shfl_xor(mx, 32));
;     const float mn = fmaxf(m, mx);
;     const float alpha = __builtin_amdgcn_exp2f(m - mn);
;     m = mn;
;     float ps = 0.f;
; #pragma unroll
;     for (int g = 0; g < 16; ++g) { sa[g] = __builtin_amdgcn_exp2f(sa[g] - mn); ps += sa[g]; }
; #pragma unroll
;     for (int g = 0; g < 16; ++g) { sb[g] = __builtin_amdgcn_exp2f(sb[g] - mn); ps += sb[g]; }
;     l = l * alpha + ps;
.LBB0_617:
	ds_read_b128 v[34:37], v130 offset:32768
	ds_read_b128 v[38:41], v130 offset:39424
	ds_read_b128 v[42:45], v130 offset:32800
	s_waitcnt lgkmcnt(2)
	v_mfma_f32_32x32x16_bf16 v[184:199], v[34:37], v[66:69], 0
	ds_read_b128 v[34:37], v130 offset:39456
	v_max3_f32 v137, v50, v51, v52
	v_max3_f32 v137, v137, v53, v54
	v_max3_f32 v137, v137, v55, v56
	v_max3_f32 v137, v137, v57, v58
	s_waitcnt lgkmcnt(2)
	v_mfma_f32_32x32x16_bf16 v[146:161], v[38:41], v[66:69], 0
	ds_read_b128 v[38:41], v130 offset:32832
	v_max3_f32 v137, v137, v59, v60
	v_max3_f32 v137, v137, v61, v62
	v_max3_f32 v137, v137, v63, v64
	v_max3_f32 v137, v137, v65, v218
	s_waitcnt lgkmcnt(2)
	v_mfma_f32_32x32x16_bf16 v[184:199], v[42:45], v[70:73], v[184:199]
	ds_read_b128 v[42:45], v130 offset:39488
	v_max3_f32 v137, v137, v219, v220
	v_max3_f32 v137, v137, v221, v222
	v_max3_f32 v137, v137, v223, v224
	v_max3_f32 v137, v137, v225, v226
	s_waitcnt lgkmcnt(2)
	v_mfma_f32_32x32x16_bf16 v[146:161], v[34:37], v[70:73], v[146:161]
	ds_read_b128 v[34:37], v130 offset:32864
	v_max3_f32 v137, v137, v227, v228
	v_max3_f32 v137, v137, v229, v230
	v_max3_f32 v137, v137, v231, v232
	v_max3_f32 v137, v137, v233, v233
	s_waitcnt lgkmcnt(2)
	v_mfma_f32_32x32x16_bf16 v[184:199], v[38:41], v[74:77], v[184:199]
	ds_read_b128 v[38:41], v130 offset:39520
	v_mov_b32_e32 v139, v137
	s_nop 1
	v_permlane32_swap_b32 v137, v139
	s_nop 1
	s_waitcnt lgkmcnt(2)
	v_mfma_f32_32x32x16_bf16 v[146:161], v[42:45], v[74:77], v[146:161]
	ds_read_b128 v[42:45], v130 offset:32896
	v_max3_f32 v135, v134, v137, v139
	v_sub_f32_e32 v141, v134, v135
	v_exp_f32_e32 v140, v141
	v_mov_b32_e32 v144, v135
	s_waitcnt lgkmcnt(2)
	v_mfma_f32_32x32x16_bf16 v[184:199], v[34:37], v[78:81], v[184:199]
	ds_read_b128 v[34:37], v130 offset:39552
	v_mov_b32_e32 v145, v135
	v_sub_f32_e32 v50, v50, v135
	v_sub_f32_e32 v51, v51, v135
	v_sub_f32_e32 v52, v52, v135
	s_waitcnt lgkmcnt(2)
	v_mfma_f32_32x32x16_bf16 v[146:161], v[38:41], v[78:81], v[146:161]
	ds_read_b128 v[38:41], v130 offset:32928
	v_sub_f32_e32 v53, v53, v135
	v_sub_f32_e32 v54, v54, v135
	v_sub_f32_e32 v55, v55, v135
	v_sub_f32_e32 v56, v56, v135
	s_waitcnt lgkmcnt(2)
	v_mfma_f32_32x32x16_bf16 v[184:199], v[42:45], v[82:85], v[184:199]
	ds_read_b128 v[42:45], v130 offset:39584
	v_sub_f32_e32 v57, v57, v135
	v_exp_f32_e32 v50, v50
	v_sub_f32_e32 v58, v58, v135
	v_sub_f32_e32 v59, v59, v135
	s_waitcnt lgkmcnt(2)
	v_mfma_f32_32x32x16_bf16 v[146:161], v[34:37], v[82:85], v[146:161]
	v_sub_f32_e32 v60, v60, v135
	v_sub_f32_e32 v61, v61, v135
	v_exp_f32_e32 v51, v51
	v_sub_f32_e32 v62, v62, v135
	s_waitcnt lgkmcnt(1)
	v_mfma_f32_32x32x16_bf16 v[184:199], v[38:41], v[86:89], v[184:199]
	v_sub_f32_e32 v63, v63, v135
	v_sub_f32_e32 v64, v64, v135
	v_sub_f32_e32 v65, v65, v135
	v_exp_f32_e32 v52, v52
	s_waitcnt lgkmcnt(0)
	v_mfma_f32_32x32x16_bf16 v[146:161], v[42:45], v[86:89], v[146:161]
	ds_read_b64_tr_b16 v[46:47], v133 offset:13312
	ds_read_b64_tr_b16 v[48:49], v133 offset:14848
	ds_read_b64_tr_b16 v[200:201], v133 offset:13376
	ds_read_b64_tr_b16 v[202:203], v133 offset:14912
	ds_read_b64_tr_b16 v[204:205], v133 offset:16384
	ds_read_b64_tr_b16 v[206:207], v133 offset:17920
	v_sub_f32_e32 v218, v218, v135
	v_sub_f32_e32 v219, v219, v135
	v_sub_f32_e32 v220, v220, v135
	v_sub_f32_e32 v221, v221, v135
	v_exp_f32_e32 v53, v53
	v_sub_f32_e32 v222, v222, v135
	v_sub_f32_e32 v223, v223, v135
	v_sub_f32_e32 v224, v224, v135
	v_sub_f32_e32 v225, v225, v135
	v_exp_f32_e32 v54, v54
	v_mul_f32_e32 v33, v140, v33
	v_mul_f32_e32 v32, v140, v32
	v_mul_f32_e32 v31, v140, v31
	v_mul_f32_e32 v30, v140, v30
	v_exp_f32_e32 v55, v55
	v_mul_f32_e32 v29, v140, v29
	v_mul_f32_e32 v28, v140, v28
	v_mul_f32_e32 v27, v140, v27
	v_mul_f32_e32 v26, v140, v26
	v_exp_f32_e32 v56, v56
	v_mul_f32_e32 v25, v140, v25
	v_mul_f32_e32 v24, v140, v24
	v_mul_f32_e32 v23, v140, v23
	v_mul_f32_e32 v22, v140, v22
	v_exp_f32_e32 v57, v57
	v_mul_f32_e32 v21, v140, v21
	v_mul_f32_e32 v20, v140, v20
	v_mul_f32_e32 v19, v140, v19
	v_mul_f32_e32 v18, v140, v18
	v_exp_f32_e32 v58, v58
	v_sub_f32_e32 v226, v226, v135
	v_sub_f32_e32 v227, v227, v135
	v_sub_f32_e32 v228, v228, v135
	v_sub_f32_e32 v229, v229, v135
	v_sub_f32_e32 v230, v230, v135
	v_exp_f32_e32 v59, v59
	v_sub_f32_e32 v231, v231, v135
	v_sub_f32_e32 v232, v232, v135
	v_sub_f32_e32 v233, v233, v135
	v_mul_f32_e32 v17, v140, v17
	v_mul_f32_e32 v16, v140, v16
	v_exp_f32_e32 v60, v60
	v_mul_f32_e32 v15, v140, v15
	v_mul_f32_e32 v14, v140, v14
	v_mul_f32_e32 v13, v140, v13
	v_mul_f32_e32 v12, v140, v12
	v_mul_f32_e32 v11, v140, v11
	v_exp_f32_e32 v61, v61
	v_mul_f32_e32 v10, v140, v10
	v_mul_f32_e32 v9, v140, v9
	v_mul_f32_e32 v8, v140, v8
	v_mul_f32_e32 v7, v140, v7
	v_mul_f32_e32 v6, v140, v6
	v_exp_f32_e32 v62, v62
	v_mul_f32_e32 v5, v140, v5
	v_mul_f32_e32 v4, v140, v4
	v_mul_f32_e32 v3, v140, v3
	v_mul_f32_e32 v2, v140, v2
	v_add_f32_e32 v238, v50, v51
	v_exp_f32_e32 v63, v63
	v_add_f32_e32 v238, v238, v52
	v_add_f32_e32 v238, v238, v53
	v_add_f32_e32 v238, v238, v54
	v_add_f32_e32 v238, v238, v55
	v_add_f32_e32 v238, v238, v56
	v_exp_f32_e32 v64, v64
	v_add_f32_e32 v238, v238, v57
	v_cvt_pk_bf16_f32 v50, v50, v51
	v_cvt_pk_bf16_f32 v51, v52, v53
	v_cvt_pk_bf16_f32 v52, v54, v55
	v_cvt_pk_bf16_f32 v53, v56, v57
	v_exp_f32_e32 v65, v65
	s_nop 0
	s_waitcnt lgkmcnt(4)
; #define MFMA(a, b, c) __builtin_amdgcn_mfma_f32_32x32x16_bf16((a), (b), (c), 0, 0, 0)
; #define ATT_VTR(p) __builtin_bit_cast(s16x4, __builtin_amdgcn_ds_read_tr16_b64_v4i16((__attribute__((address_space(3))) v4i16_t*)(p)))
; template <int DQK>
; DI void attn_tile(const u16* __restrict__ q, int ldq, int qpos0, const Seg& s0, const Seg& s1, int nseg, bool has_sink,
;                   float sinkl2, u16* __restrict__ out, int ldo, char* lds) {
;     ...
;     float ps = 0.f;
; #pragma unroll
;     for (int g = 0; g < 16; ++g) { sa[g] = __builtin_amdgcn_exp2f(sa[g] - mn); ps += sa[g]; }
; #pragma unroll
;     for (int g = 0; g < 16; ++g) { sb[g] = __builtin_amdgcn_exp2f(sb[g] - mn); ps += sb[g]; }
;     l = l * alpha + ps;
; #pragma unroll
;     for (int g = 0; g < 16; ++g) { o0[g] *= alpha; o1[g] *= alpha; }
; #pragma unroll
;     for (int kt = 0; kt < 2; ++kt) {
; #pragma unroll
;       for (int s = 0; s < 2; ++s) {
;         const f32x16& sv = kt == 0 ? sa : sb;
;         uint4 pu;
;         pu.x = pack2(sv[8 * s + 0], sv[8 * s + 1]); pu.y = pack2(sv[8 * s + 2], sv[8 * s + 3]);
;         pu.z = pack2(sv[8 * s + 4], sv[8 * s + 5]); pu.w = pack2(sv[8 * s + 6], sv[8 * s + 7]);
;         bf16x8 pf = __builtin_bit_cast(bf16x8, pu);
;         const lds_cptr vp = vp0 + (kt * 32 + 16 * s) * (VST * 2);
;         {
;           s16x4 lo = ATT_VTR(vp);
;           s16x4 hi = ATT_VTR(vp + 8 * VST * 2);
;           bf16x8 vf = __builtin_shufflevector(lo, hi, 0, 1, 2, 3, 4, 5, 6, 7);
;           o0 = MFMA(vf, pf, o0);
;         }
;         {
;           s16x4 lo = ATT_VTR(vp + 64);
;           s16x4 hi = ATT_VTR(vp + 8 * VST * 2 + 64);
;           bf16x8 vf = __builtin_shufflevector(lo, hi, 0, 1, 2, 3, 4, 5, 6, 7);
;           o1 = MFMA(vf, pf, o1);
;         }
;       }
;     }
;     ...
;     __syncthreads();
;     ATT_STOREX(kreg0, kreg1, vreg0);
;     __syncthreads();
;     if (i + 2 < NT) ATT_LOADX(i + 2, kreg0, kreg1, vreg0);
;     compute(i);
;     __syncthreads();
;     ATT_STOREX(krgB0, krgB1, vrgB0);
;     __syncthreads();
;     if (i + 3 < NT) ATT_LOADX(i + 3, krgB0, krgB1, vrgB0);
	v_mfma_f32_32x32x16_bf16 v[18:33], v[46:49], v[50:53], v[18:33]
	ds_read_b64_tr_b16 v[46:47], v133 offset:16448
	ds_read_b64_tr_b16 v[48:49], v133 offset:17984
	s_waitcnt lgkmcnt(4)
	v_mfma_f32_32x32x16_bf16 v[2:17], v[200:203], v[50:53], v[2:17]
	ds_read_b64_tr_b16 v[200:201], v133 offset:19456
	ds_read_b64_tr_b16 v[202:203], v133 offset:20992
	v_exp_f32_e32 v218, v218
	v_add_f32_e32 v238, v238, v58
	v_add_f32_e32 v238, v238, v59
	v_exp_f32_e32 v219, v219
	v_add_f32_e32 v238, v238, v60
	v_add_f32_e32 v238, v238, v61
	v_exp_f32_e32 v220, v220
	v_add_f32_e32 v238, v238, v62
	v_add_f32_e32 v238, v238, v63
	v_exp_f32_e32 v221, v221
	v_add_f32_e32 v238, v238, v64
	v_add_f32_e32 v238, v238, v65
	v_exp_f32_e32 v222, v222
	v_cvt_pk_bf16_f32 v54, v58, v59
	v_cvt_pk_bf16_f32 v55, v60, v61
	v_exp_f32_e32 v223, v223
	v_cvt_pk_bf16_f32 v56, v62, v63
	v_cvt_pk_bf16_f32 v57, v64, v65
	v_exp_f32_e32 v224, v224
	v_exp_f32_e32 v225, v225
	s_nop 0
	s_waitcnt lgkmcnt(4)
	v_mfma_f32_32x32x16_bf16 v[18:33], v[204:207], v[54:57], v[18:33]
	ds_read_b64_tr_b16 v[204:205], v133 offset:19520
	ds_read_b64_tr_b16 v[206:207], v133 offset:21056
	s_waitcnt lgkmcnt(4)
	v_mfma_f32_32x32x16_bf16 v[2:17], v[46:49], v[54:57], v[2:17]
	ds_read_b64_tr_b16 v[46:47], v133 offset:22528
	ds_read_b64_tr_b16 v[48:49], v133 offset:24064
	v_exp_f32_e32 v226, v226
	v_add_f32_e32 v238, v238, v218
	v_add_f32_e32 v238, v238, v219
	v_exp_f32_e32 v227, v227
	v_add_f32_e32 v238, v238, v220
	v_add_f32_e32 v238, v238, v221
	v_exp_f32_e32 v228, v228
	v_add_f32_e32 v238, v238, v222
	v_add_f32_e32 v238, v238, v223
	v_exp_f32_e32 v229, v229
	v_add_f32_e32 v238, v238, v224
	v_add_f32_e32 v238, v238, v225
	v_exp_f32_e32 v230, v230
	v_cvt_pk_bf16_f32 v218, v218, v219
	v_cvt_pk_bf16_f32 v219, v220, v221
	v_exp_f32_e32 v231, v231
	v_cvt_pk_bf16_f32 v220, v222, v223
	v_cvt_pk_bf16_f32 v221, v224, v225
	v_exp_f32_e32 v232, v232
	v_exp_f32_e32 v233, v233
	s_nop 0
	s_waitcnt lgkmcnt(4)
	v_mfma_f32_32x32x16_bf16 v[18:33], v[200:203], v[218:221], v[18:33]
	ds_read_b64_tr_b16 v[200:201], v133 offset:22592
	ds_read_b64_tr_b16 v[202:203], v133 offset:24128
	s_waitcnt lgkmcnt(4)
	v_mfma_f32_32x32x16_bf16 v[2:17], v[204:207], v[218:221], v[2:17]
	v_add_f32_e32 v238, v238, v226
	v_add_f32_e32 v238, v238, v227
	v_add_f32_e32 v238, v238, v228
	v_add_f32_e32 v238, v238, v229
	v_add_f32_e32 v238, v238, v230
	v_add_f32_e32 v238, v238, v231
	v_add_f32_e32 v238, v238, v232
	v_add_f32_e32 v238, v238, v233
	v_cvt_pk_bf16_f32 v222, v226, v227
	v_cvt_pk_bf16_f32 v223, v228, v229
	v_cvt_pk_bf16_f32 v224, v230, v231
	v_cvt_pk_bf16_f32 v225, v232, v233
	s_nop 0
	s_waitcnt lgkmcnt(2)
	v_mfma_f32_32x32x16_bf16 v[18:33], v[46:49], v[222:225], v[18:33]
	s_waitcnt lgkmcnt(0)
	v_mfma_f32_32x32x16_bf16 v[2:17], v[200:203], v[222:225], v[2:17]
	v_fma_f32 v136, v128, v140, v238
	s_waitcnt vmcnt(0)
	ds_write_b128 v121, v[90:93]
	s_and_saveexec_b64 s[4:5], s[0:1]
	ds_write_b128 v129, v[94:97]
	s_or_b64 exec, exec, s[4:5]
	s_cmp_gt_u32 s27, 64
	ds_write_b128 v132, v[110:113] offset:46080
	s_waitcnt lgkmcnt(0)
	s_barrier
	s_cbranch_scc1 .LBB0_602
	s_cmp_lt_u32 s27, 61
	s_cselect_b64 s[4:5], -1, 0
	s_and_b64 s[16:17], s[4:5], exec
	s_cselect_b32 s16, 0, 0x3ffffc0
	s_add_i32 s16, s16, s22
	s_lshl_b32 s28, s16, 6
	v_add_u32_e32 v36, s28, v116
	v_ashrrev_i32_e32 v37, 31, v36
	s_and_saveexec_b64 s[16:17], vcc
	s_xor_b64 s[16:17], exec, s[16:17]
	s_cbranch_execz .LBB0_623
	s_and_b64 s[18:19], s[4:5], exec
	s_cselect_b32 s19, s15, s11
	s_cselect_b32 s18, s14, s10
	v_lshlrev_b64 v[36:37], 6, v[36:37]
	v_lshl_add_u64 v[36:37], s[18:19], 0, v[36:37]
	s_movk_i32 s18, 0xff80
	v_lshl_add_u64 v[36:37], v[124:125], 1, v[36:37]
	s_mov_b32 s19, -1
	v_lshl_add_u64 v[38:39], v[36:37], 0, s[18:19]
	s_andn2_saveexec_b64 s[16:17], s[16:17]
	s_cbranch_execnz .LBB0_624
